# gMLP V^T staging: 12 loads per group in flight with counted vmcnt; SwiGLU epilogue rstd values prefetched from LDS once per unit
# baseline (speedup 1.0000x reference)
.LBB0_348:
	ds_read_b32 v1, v54 offset:34816
	v_lshl_add_u64 v[6:7], v[44:45], 0, s[94:95]
	global_load_dwordx4 v[100:103], v[38:39], off offset:-240
	global_load_dwordx4 v[104:107], v[38:39], off offset:-256
	global_load_dwordx4 v[108:111], v[6:7], off offset:-128
	global_load_dwordx4 v[112:115], v[38:39], off offset:-112
	global_load_dwordx4 v[116:119], v[38:39], off offset:-128
	global_load_dwordx4 v[120:123], v[6:7], off offset:-64
	global_load_dwordx4 v[124:127], v[38:39], off offset:16
	global_load_dwordx4 v[128:131], v[38:39], off
	global_load_dwordx4 v[132:135], v[6:7], off
	global_load_dwordx4 v[136:139], v[38:39], off offset:144
	global_load_dwordx4 v[140:143], v[38:39], off offset:128
	global_load_dwordx4 v[144:147], v[6:7], off offset:64
	s_waitcnt vmcnt(9)
	v_mov_b64_e32 v[2:3], v[100:101]
	v_mov_b64_e32 v[4:5], v[102:103]
	v_mov_b64_e32 v[8:9], v[104:105]
	v_mov_b64_e32 v[10:11], v[106:107]
	v_mov_b64_e32 v[12:13], v[108:109]
	v_mov_b64_e32 v[14:15], v[110:111]
	v_ashrrev_i32_e32 v37, 31, v36
	v_lshlrev_b32_e32 v16, 16, v12
	s_waitcnt lgkmcnt(0)
	v_mul_f32_e32 v16, v1, v16
	v_mul_f32_e32 v8, v8, v16
	v_bfe_u32 v16, v8, 16, 1
	v_add3_u32 v8, v8, v16, s93
	ds_write_b16_d16_hi v55, v8
	v_and_b32_e32 v8, 0xffff0000, v12
	v_mul_f32_e32 v8, v1, v8
	v_mul_f32_e32 v8, v9, v8
	v_bfe_u32 v9, v8, 16, 1
	v_add3_u32 v8, v8, v9, s93
	ds_write_b16_d16_hi v55, v8 offset:272
	v_lshlrev_b32_e32 v8, 16, v13
	v_mul_f32_e32 v8, v1, v8
	v_mul_f32_e32 v8, v10, v8
	v_bfe_u32 v9, v8, 16, 1
	v_add3_u32 v8, v8, v9, s93
	ds_write_b16_d16_hi v55, v8 offset:544
	v_and_b32_e32 v8, 0xffff0000, v13
	v_mul_f32_e32 v8, v1, v8
	v_mul_f32_e32 v8, v11, v8
	v_bfe_u32 v9, v8, 16, 1
	v_add3_u32 v8, v8, v9, s93
	ds_write_b16_d16_hi v55, v8 offset:816
	v_lshlrev_b32_e32 v8, 16, v14
	v_mul_f32_e32 v8, v1, v8
	v_mul_f32_e32 v2, v2, v8
	v_bfe_u32 v8, v2, 16, 1
	v_add3_u32 v2, v2, v8, s93
	ds_write_b16_d16_hi v55, v2 offset:1088
	v_and_b32_e32 v2, 0xffff0000, v14
	v_mul_f32_e32 v2, v1, v2
	v_mul_f32_e32 v2, v2, v3
	v_bfe_u32 v3, v2, 16, 1
	v_add3_u32 v2, v2, v3, s93
	ds_write_b16_d16_hi v55, v2 offset:1360
	v_lshlrev_b32_e32 v2, 16, v15
	v_mul_f32_e32 v2, v1, v2
	v_mul_f32_e32 v2, v2, v4
	v_bfe_u32 v3, v2, 16, 1
	v_add3_u32 v2, v2, v3, s93
	ds_write_b16_d16_hi v55, v2 offset:1632
	v_and_b32_e32 v2, 0xffff0000, v15
	v_mul_f32_e32 v2, v1, v2
	v_mul_f32_e32 v2, v2, v5
	v_bfe_u32 v3, v2, 16, 1
	v_add3_u32 v2, v2, v3, s93
	ds_write_b16_d16_hi v56, v2
	s_waitcnt vmcnt(6)
	v_mov_b64_e32 v[2:3], v[112:113]
	v_mov_b64_e32 v[4:5], v[114:115]
	v_mov_b64_e32 v[8:9], v[116:117]
	v_mov_b64_e32 v[10:11], v[118:119]
	v_mov_b64_e32 v[12:13], v[120:121]
	v_mov_b64_e32 v[14:15], v[122:123]
	v_lshlrev_b32_e32 v16, 16, v12
	v_mul_f32_e32 v16, v1, v16
	v_mul_f32_e32 v8, v8, v16
	v_bfe_u32 v16, v8, 16, 1
	v_add3_u32 v8, v8, v16, s93
	ds_write_b16_d16_hi v55, v8 offset:8704
	v_and_b32_e32 v8, 0xffff0000, v12
	v_mul_f32_e32 v8, v1, v8
	v_mul_f32_e32 v8, v9, v8
	v_bfe_u32 v9, v8, 16, 1
	v_add3_u32 v8, v8, v9, s93
	ds_write_b16_d16_hi v55, v8 offset:8976
	v_lshlrev_b32_e32 v8, 16, v13
	v_mul_f32_e32 v8, v1, v8
	v_mul_f32_e32 v8, v10, v8
	v_bfe_u32 v9, v8, 16, 1
	v_add3_u32 v8, v8, v9, s93
	ds_write_b16_d16_hi v55, v8 offset:9248
	v_and_b32_e32 v8, 0xffff0000, v13
	v_mul_f32_e32 v8, v1, v8
	v_mul_f32_e32 v8, v11, v8
	v_bfe_u32 v9, v8, 16, 1
	v_add3_u32 v8, v8, v9, s93
	ds_write_b16_d16_hi v55, v8 offset:9520
	v_lshlrev_b32_e32 v8, 16, v14
	v_mul_f32_e32 v8, v1, v8
	v_mul_f32_e32 v2, v2, v8
	v_bfe_u32 v8, v2, 16, 1
	v_add3_u32 v2, v2, v8, s93
	ds_write_b16_d16_hi v55, v2 offset:9792
	v_and_b32_e32 v2, 0xffff0000, v14
	v_mul_f32_e32 v2, v1, v2
	v_mul_f32_e32 v2, v2, v3
	v_bfe_u32 v3, v2, 16, 1
	v_add3_u32 v2, v2, v3, s93
	ds_write_b16_d16_hi v55, v2 offset:10064
	v_lshlrev_b32_e32 v2, 16, v15
	v_mul_f32_e32 v2, v1, v2
	v_mul_f32_e32 v2, v2, v4
	v_bfe_u32 v3, v2, 16, 1
	v_add3_u32 v2, v2, v3, s93
	ds_write_b16_d16_hi v55, v2 offset:10336
	v_and_b32_e32 v2, 0xffff0000, v15
	v_mul_f32_e32 v2, v1, v2
	v_mul_f32_e32 v2, v2, v5
	v_bfe_u32 v3, v2, 16, 1
	v_add3_u32 v2, v2, v3, s93
	ds_write_b16_d16_hi v55, v2 offset:10608
	s_waitcnt vmcnt(3)
	v_mov_b64_e32 v[2:3], v[124:125]
	v_mov_b64_e32 v[4:5], v[126:127]
	v_mov_b64_e32 v[8:9], v[128:129]
	v_mov_b64_e32 v[10:11], v[130:131]
	v_mov_b64_e32 v[12:13], v[132:133]
	v_mov_b64_e32 v[14:15], v[134:135]
	v_lshlrev_b32_e32 v16, 16, v12
	v_mul_f32_e32 v16, v1, v16
	v_mul_f32_e32 v8, v8, v16
	v_bfe_u32 v16, v8, 16, 1
	v_add3_u32 v8, v8, v16, s93
	ds_write_b16_d16_hi v55, v8 offset:17408
	v_and_b32_e32 v8, 0xffff0000, v12
	v_mul_f32_e32 v8, v1, v8
	v_mul_f32_e32 v8, v9, v8
	v_bfe_u32 v9, v8, 16, 1
	v_add3_u32 v8, v8, v9, s93
	ds_write_b16_d16_hi v55, v8 offset:17680
	v_lshlrev_b32_e32 v8, 16, v13
	v_mul_f32_e32 v8, v1, v8
	v_mul_f32_e32 v8, v10, v8
	v_bfe_u32 v9, v8, 16, 1
	v_add3_u32 v8, v8, v9, s93
	ds_write_b16_d16_hi v55, v8 offset:17952
	v_and_b32_e32 v8, 0xffff0000, v13
	v_mul_f32_e32 v8, v1, v8
	v_mul_f32_e32 v8, v11, v8
	v_bfe_u32 v9, v8, 16, 1
	v_add3_u32 v8, v8, v9, s93
	ds_write_b16_d16_hi v55, v8 offset:18224
	v_lshlrev_b32_e32 v8, 16, v14
	v_mul_f32_e32 v8, v1, v8
	v_mul_f32_e32 v2, v2, v8
	v_bfe_u32 v8, v2, 16, 1
	v_add3_u32 v2, v2, v8, s93
	ds_write_b16_d16_hi v55, v2 offset:18496
	v_and_b32_e32 v2, 0xffff0000, v14
	v_mul_f32_e32 v2, v1, v2
	v_mul_f32_e32 v2, v2, v3
	v_bfe_u32 v3, v2, 16, 1
	v_add3_u32 v2, v2, v3, s93
	ds_write_b16_d16_hi v55, v2 offset:18768
	v_lshlrev_b32_e32 v2, 16, v15
	v_mul_f32_e32 v2, v1, v2
	v_mul_f32_e32 v2, v2, v4
	v_bfe_u32 v3, v2, 16, 1
	v_add3_u32 v2, v2, v3, s93
	ds_write_b16_d16_hi v55, v2 offset:19040
	v_and_b32_e32 v2, 0xffff0000, v15
	v_mul_f32_e32 v2, v1, v2
	v_mul_f32_e32 v2, v2, v5
	v_bfe_u32 v3, v2, 16, 1
	v_add3_u32 v2, v2, v3, s93
	ds_write_b16_d16_hi v55, v2 offset:19312
	s_waitcnt vmcnt(0)
	v_mov_b64_e32 v[2:3], v[136:137]
	v_mov_b64_e32 v[4:5], v[138:139]
	v_mov_b64_e32 v[10:11], v[140:141]
	v_mov_b64_e32 v[12:13], v[142:143]
	s_nop 0
	v_mov_b64_e32 v[6:7], v[144:145]
	v_mov_b64_e32 v[8:9], v[146:147]
	v_lshlrev_b32_e32 v14, 16, v6
	v_mul_f32_e32 v14, v1, v14
	v_mul_f32_e32 v10, v10, v14
	v_and_b32_e32 v6, 0xffff0000, v6
	v_bfe_u32 v14, v10, 16, 1
	v_mul_f32_e32 v6, v1, v6
	v_add3_u32 v10, v10, v14, s93
	v_mul_f32_e32 v6, v11, v6
	ds_write_b16_d16_hi v55, v10 offset:26112
	v_bfe_u32 v10, v6, 16, 1
	v_add3_u32 v6, v6, v10, s93
	ds_write_b16_d16_hi v55, v6 offset:26384
	v_lshlrev_b32_e32 v6, 16, v7
	v_mul_f32_e32 v6, v1, v6
	v_mul_f32_e32 v6, v12, v6
	v_bfe_u32 v10, v6, 16, 1
	v_add3_u32 v6, v6, v10, s93
	ds_write_b16_d16_hi v55, v6 offset:26656
	v_and_b32_e32 v6, 0xffff0000, v7
	v_mul_f32_e32 v6, v1, v6
	v_mul_f32_e32 v6, v13, v6
	v_bfe_u32 v7, v6, 16, 1
	v_add3_u32 v6, v6, v7, s93
	ds_write_b16_d16_hi v55, v6 offset:26928
	v_lshlrev_b32_e32 v6, 16, v8
	v_mul_f32_e32 v6, v1, v6
	v_mul_f32_e32 v2, v2, v6
	v_bfe_u32 v6, v2, 16, 1
	v_add3_u32 v2, v2, v6, s93
	ds_write_b16_d16_hi v55, v2 offset:27200
	v_and_b32_e32 v2, 0xffff0000, v8
	v_mul_f32_e32 v2, v1, v2
	v_mul_f32_e32 v2, v2, v3
	v_bfe_u32 v3, v2, 16, 1
	v_add3_u32 v2, v2, v3, s93
	ds_write_b16_d16_hi v55, v2 offset:27472
	v_lshlrev_b32_e32 v2, 16, v9
	v_mul_f32_e32 v2, v1, v2
	v_mul_f32_e32 v2, v2, v4
	v_bfe_u32 v3, v2, 16, 1
	v_add3_u32 v2, v2, v3, s93
	ds_write_b16_d16_hi v55, v2 offset:27744
	v_and_b32_e32 v2, 0xffff0000, v9
	v_mul_f32_e32 v1, v1, v2
	v_mul_f32_e32 v1, v1, v5
	v_bfe_u32 v2, v1, 16, 1
	v_add3_u32 v1, v1, v2, s93
	v_lshlrev_b64 v[2:3], 9, v[36:37]
	v_lshl_add_u64 v[46:47], v[34:35], 0, v[2:3]
	v_mov_b32_e32 v2, v0
	v_mov_b32_e32 v3, v0
	ds_write_b16_d16_hi v55, v1 offset:28016
	v_mov_b32_e32 v1, v0
	v_mov_b64_e32 v[32:33], v[2:3]
	v_mov_b64_e32 v[28:29], v[2:3]
	v_mov_b64_e32 v[24:25], v[2:3]
	v_mov_b64_e32 v[20:21], v[2:3]
	v_mov_b64_e32 v[16:17], v[2:3]
	v_mov_b64_e32 v[12:13], v[2:3]
	v_mov_b64_e32 v[8:9], v[2:3]
	v_mov_b64_e32 v[30:31], v[0:1]
	v_mov_b64_e32 v[26:27], v[0:1]
	v_mov_b64_e32 v[22:23], v[0:1]
	v_mov_b64_e32 v[18:19], v[0:1]
	v_mov_b64_e32 v[14:15], v[0:1]
	v_mov_b64_e32 v[10:11], v[0:1]
	v_mov_b64_e32 v[6:7], v[0:1]
	v_mov_b64_e32 v[4:5], v[2:3]
	v_mov_b64_e32 v[2:3], v[0:1]
	s_waitcnt lgkmcnt(0)
	s_barrier
	s_and_saveexec_b64 s[82:83], vcc
	s_cbranch_execz .LBB0_352
	global_load_dwordx4 v[2:5], v[46:47], off
	global_load_dwordx4 v[6:9], v[46:47], off offset:16
	s_mov_b32 s1, 0x5040100
	ds_read_b128 v[10:13], v57
	ds_read_b128 v[14:17], v57 offset:4352
	ds_read_b128 v[48:51], v57 offset:30464
	s_waitcnt vmcnt(1)
	v_cndmask_b32_e64 v1, v2, 0, s[10:11]
	v_cndmask_b32_e64 v2, 0, v3, s[12:13]
	v_cvt_pk_bf16_f32 v3, v4, v5
	s_waitcnt vmcnt(0)
	v_cvt_pk_bf16_f32 v4, v6, v7
	v_cvt_pk_bf16_f32 v5, v8, v9
	v_cndmask_b32_e64 v6, v4, 0, s[20:21]
	v_lshrrev_b32_e32 v4, 16, v4
	v_cndmask_b32_e64 v7, v5, 0, s[24:25]
	v_lshrrev_b32_e32 v5, 16, v5
	v_cndmask_b32_e64 v4, v4, 0, s[18:19]
	v_cndmask_b32_e64 v5, v5, 0, s[22:23]
	v_perm_b32 v4, v4, v6, s1
	v_perm_b32 v5, v5, v7, s1
	ds_read_b128 v[6:9], v57 offset:8704
	v_cvt_pk_bf16_f32 v2, v1, v2
	v_cndmask_b32_e64 v1, v3, 0, s[16:17]
	v_lshrrev_b32_e32 v3, 16, v3
	v_cndmask_b32_e64 v3, v3, 0, s[14:15]
	v_perm_b32 v3, v3, v1, s1
	s_waitcnt lgkmcnt(3)
	s_nop 0
	v_mfma_f32_16x16x32_bf16 v[30:33], v[10:13], v[2:5], 0
	ds_read_b128 v[10:13], v57 offset:13056
	s_waitcnt lgkmcnt(1)
	v_mfma_f32_16x16x32_bf16 v[22:25], v[6:9], v[2:5], 0
	ds_read_b128 v[6:9], v57 offset:17408
	v_mfma_f32_16x16x32_bf16 v[26:29], v[14:17], v[2:5], 0
	s_waitcnt lgkmcnt(1)
	v_mfma_f32_16x16x32_bf16 v[18:21], v[10:13], v[2:5], 0
	ds_read_b128 v[10:13], v57 offset:21760
	s_waitcnt lgkmcnt(1)
	v_mfma_f32_16x16x32_bf16 v[14:17], v[6:9], v[2:5], 0
	ds_read_b128 v[6:9], v57 offset:26112
	s_waitcnt lgkmcnt(1)
	v_mfma_f32_16x16x32_bf16 v[10:13], v[10:13], v[2:5], 0
	s_waitcnt lgkmcnt(0)
	v_mfma_f32_16x16x32_bf16 v[6:9], v[6:9], v[2:5], 0
	v_mfma_f32_16x16x32_bf16 v[2:5], v[48:51], v[2:5], 0
	s_or_b64 exec, exec, s[82:83]
	s_and_saveexec_b64 s[82:83], s[26:27]
	s_cbranch_execnz .LBB0_353

.LBB0_355:
	global_load_dwordx4 v[48:51], v[46:47], off offset:384
	global_load_dwordx4 v[58:61], v[46:47], off offset:400
	s_mov_b32 s1, 0x5040100
	s_waitcnt vmcnt(1)
	v_cndmask_b32_e64 v1, v48, 0, s[66:67]
	v_cndmask_b32_e64 v46, 0, v49, s[68:69]
	v_cvt_pk_bf16_f32 v46, v1, v46
	v_cvt_pk_bf16_f32 v1, v50, v51
	v_cndmask_b32_e64 v47, v1, 0, s[72:73]
	v_lshrrev_b32_e32 v1, 16, v1
	ds_read_b128 v[50:53], v57 offset:192
	v_cndmask_b32_e64 v1, v1, 0, s[70:71]
	v_perm_b32 v47, v1, v47, s1
	s_waitcnt vmcnt(0)
	v_cvt_pk_bf16_f32 v1, v58, v59
	v_cndmask_b32_e64 v48, v1, 0, s[76:77]
	v_lshrrev_b32_e32 v1, 16, v1
	v_cndmask_b32_e64 v1, v1, 0, s[74:75]
	v_perm_b32 v48, v1, v48, s1
	v_cvt_pk_bf16_f32 v1, v60, v61
	v_cndmask_b32_e64 v49, v1, 0, s[80:81]
	v_lshrrev_b32_e32 v1, 16, v1
	v_cndmask_b32_e64 v1, v1, 0, s[78:79]
	v_perm_b32 v49, v1, v49, s1
	s_waitcnt lgkmcnt(0)
	s_nop 0
	v_mfma_f32_16x16x32_bf16 v[30:33], v[50:53], v[46:49], v[30:33]
	ds_read_b128 v[50:53], v57 offset:4544
	ds_read_b128 v[244:247], v57 offset:8896
	ds_read_b128 v[248:251], v57 offset:13248
	s_waitcnt lgkmcnt(2)
	v_mfma_f32_16x16x32_bf16 v[26:29], v[50:53], v[46:49], v[26:29]
	ds_read_b128 v[50:53], v57 offset:17600
	s_waitcnt lgkmcnt(2)
	v_mfma_f32_16x16x32_bf16 v[22:25], v[244:247], v[46:49], v[22:25]
	ds_read_b128 v[244:247], v57 offset:21952
	s_waitcnt lgkmcnt(2)
	v_mfma_f32_16x16x32_bf16 v[18:21], v[248:251], v[46:49], v[18:21]
	ds_read_b128 v[248:251], v57 offset:26304
	s_waitcnt lgkmcnt(2)
	v_mfma_f32_16x16x32_bf16 v[14:17], v[50:53], v[46:49], v[14:17]
	ds_read_b128 v[50:53], v57 offset:30656
	s_waitcnt lgkmcnt(2)
	v_mfma_f32_16x16x32_bf16 v[10:13], v[244:247], v[46:49], v[10:13]
	s_waitcnt lgkmcnt(1)
	v_mfma_f32_16x16x32_bf16 v[6:9], v[248:251], v[46:49], v[6:9]
	s_waitcnt lgkmcnt(0)
	v_mfma_f32_16x16x32_bf16 v[2:5], v[50:53], v[46:49], v[2:5]
	s_branch .LBB0_347
	s_nop 0
	s_nop 0
	s_nop 0
	s_nop 0
	s_nop 0
	s_nop 0
	s_nop 0
	s_nop 0
	s_nop 0
	s_nop 0
	s_nop 0
	s_nop 0
	s_nop 0
	s_nop 0
	s_nop 0
	s_nop 0
	s_nop 0
	s_nop 0
	s_nop 0
	s_nop 0
	s_nop 0
	s_nop 0
	s_nop 0
	s_nop 0
	s_nop 0
	s_nop 0
	s_nop 0
	s_nop 0
	s_nop 0
	s_nop 0
	s_nop 0
	s_nop 0
	s_nop 0
	s_nop 0
	s_nop 0
	s_nop 0
	s_nop 0
	s_nop 0
	s_nop 0
	s_nop 0

.LBB0_751:
	s_add_u32 s24, s12, 0xfff80080
	s_addc_u32 s25, s13, -1
	s_add_i32 s49, 0, 0x10000
	v_add_u32_e32 v148, s49, v1
	ds_read_b128 v[144:147], v148
	ds_read_b128 v[158:161], v148 offset:1024
	ds_read_b128 v[162:165], v148 offset:2048
	ds_read_b128 v[166:169], v148 offset:3072
	s_cmp_eq_u32 s48, 28
	s_cselect_b32 s27, s19, s25
	s_cselect_b32 s26, s44, s24
	s_cselect_b32 s25, s17, s47
	s_cselect_b32 s24, s45, s46
	v_lshl_add_u64 v[210:211], s[12:13], 0, v[140:141]
	s_add_i32 m0, s39, 0xc000
	ds_read_b128 v[170:173], v156
	ds_read_b128 v[174:177], v156 offset:1024
	ds_read_b128 v[178:181], v156 offset:2048
	ds_read_b128 v[182:185], v156 offset:3072
	ds_read_b128 v[194:197], v156 offset:4096
	ds_read_b128 v[198:201], v156 offset:5120
	ds_read_b128 v[202:205], v156 offset:6144
	ds_read_b128 v[206:209], v156 offset:7168
	global_load_lds_dwordx4 v[210:211], off
	v_lshl_add_u64 v[210:211], s[12:13], 0, v[142:143]
	s_add_i32 m0, s39, 0xe000
	s_nop 0
	global_load_lds_dwordx4 v[210:211], off
	s_waitcnt lgkmcnt(8)
	s_barrier
	s_waitcnt lgkmcnt(0)
	s_setprio 1
	s_waitcnt lgkmcnt(0)
	v_mfma_f32_16x16x32_bf16 v[126:129], v[144:147], v[170:173], v[126:129]
	v_mfma_f32_16x16x32_bf16 v[118:121], v[162:165], v[170:173], v[118:121]
	v_mfma_f32_16x16x32_bf16 v[110:113], v[144:147], v[178:181], v[110:113]
	v_mfma_f32_16x16x32_bf16 v[102:105], v[162:165], v[178:181], v[102:105]
	v_mfma_f32_16x16x32_bf16 v[94:97], v[144:147], v[194:197], v[94:97]
	v_mfma_f32_16x16x32_bf16 v[86:89], v[162:165], v[194:197], v[86:89]
	v_mfma_f32_16x16x32_bf16 v[78:81], v[144:147], v[202:205], v[78:81]
	v_mfma_f32_16x16x32_bf16 v[70:73], v[162:165], v[202:205], v[70:73]
	v_mfma_f32_16x16x32_bf16 v[126:129], v[158:161], v[174:177], v[126:129]
	v_mfma_f32_16x16x32_bf16 v[118:121], v[166:169], v[174:177], v[118:121]
	v_mfma_f32_16x16x32_bf16 v[110:113], v[158:161], v[182:185], v[110:113]
	v_mfma_f32_16x16x32_bf16 v[102:105], v[166:169], v[182:185], v[102:105]
	v_mfma_f32_16x16x32_bf16 v[94:97], v[158:161], v[198:201], v[94:97]
	v_mfma_f32_16x16x32_bf16 v[86:89], v[166:169], v[198:201], v[86:89]
	v_mfma_f32_16x16x32_bf16 v[78:81], v[158:161], v[206:209], v[78:81]
	v_mfma_f32_16x16x32_bf16 v[70:73], v[166:169], v[206:209], v[70:73]
	s_setprio 0
	s_barrier
	s_add_i32 s52, 0, 0x14000
	s_add_i32 s49, s49, s34
	v_add_u32_e32 v148, s52, v1
	v_lshl_add_u64 v[220:221], s[24:25], 0, v[134:135]
	s_mov_b32 m0, s49
	ds_read_b128 v[210:213], v148
	ds_read_b128 v[236:239], v148 offset:1024
	ds_read_b128 v[240:243], v148 offset:2048
	ds_read_b128 v[244:247], v148 offset:3072
	global_load_lds_dwordx4 v[220:221], off
	v_lshl_add_u64 v[222:223], s[24:25], 0, v[130:131]
	s_add_i32 m0, s49, 0x2000
	s_nop 0
	global_load_lds_dwordx4 v[222:223], off
	s_barrier
	s_waitcnt lgkmcnt(0)
	s_setprio 1
	s_waitcnt lgkmcnt(0)
	v_mfma_f32_16x16x32_bf16 v[122:125], v[210:213], v[170:173], v[122:125]
	v_mfma_f32_16x16x32_bf16 v[114:117], v[240:243], v[170:173], v[114:117]
	v_mfma_f32_16x16x32_bf16 v[106:109], v[210:213], v[178:181], v[106:109]
	v_mfma_f32_16x16x32_bf16 v[98:101], v[240:243], v[178:181], v[98:101]
	v_mfma_f32_16x16x32_bf16 v[90:93], v[210:213], v[194:197], v[90:93]
	v_mfma_f32_16x16x32_bf16 v[82:85], v[240:243], v[194:197], v[82:85]
	v_mfma_f32_16x16x32_bf16 v[74:77], v[210:213], v[202:205], v[74:77]
	v_mfma_f32_16x16x32_bf16 v[66:69], v[240:243], v[202:205], v[66:69]
	v_mfma_f32_16x16x32_bf16 v[122:125], v[236:239], v[174:177], v[122:125]
	v_mfma_f32_16x16x32_bf16 v[114:117], v[244:247], v[174:177], v[114:117]
	v_mfma_f32_16x16x32_bf16 v[106:109], v[236:239], v[182:185], v[106:109]
	v_mfma_f32_16x16x32_bf16 v[98:101], v[244:247], v[182:185], v[98:101]
	v_mfma_f32_16x16x32_bf16 v[90:93], v[236:239], v[198:201], v[90:93]
	v_mfma_f32_16x16x32_bf16 v[82:85], v[244:247], v[198:201], v[82:85]
	v_mfma_f32_16x16x32_bf16 v[74:77], v[236:239], v[206:209], v[74:77]
	v_mfma_f32_16x16x32_bf16 v[66:69], v[244:247], v[206:209], v[66:69]
	s_setprio 0
	s_mov_b32 m0, s39
	v_lshl_add_u64 v[248:249], s[26:27], 0, v[136:137]
	s_barrier
	ds_read_b128 v[170:173], v156 offset:16384
	ds_read_b128 v[174:177], v156 offset:17408
	ds_read_b128 v[178:181], v156 offset:18432
	ds_read_b128 v[182:185], v156 offset:19456
	ds_read_b128 v[194:197], v156 offset:20480
	ds_read_b128 v[198:201], v156 offset:21504
	ds_read_b128 v[202:205], v156 offset:22528
	ds_read_b128 v[206:209], v156 offset:23552
	global_load_lds_dwordx4 v[248:249], off
	v_lshl_add_u64 v[250:251], s[26:27], 0, v[132:133]
	s_mov_b32 m0, s40
	s_nop 0
	global_load_lds_dwordx4 v[250:251], off
	s_barrier
	s_waitcnt lgkmcnt(0)
	s_setprio 1
	s_waitcnt lgkmcnt(0)
	v_mfma_f32_16x16x32_bf16 v[62:65], v[144:147], v[170:173], v[62:65]
	v_mfma_f32_16x16x32_bf16 v[54:57], v[162:165], v[170:173], v[54:57]
	v_mfma_f32_16x16x32_bf16 v[46:49], v[144:147], v[178:181], v[46:49]
	v_mfma_f32_16x16x32_bf16 v[38:41], v[162:165], v[178:181], v[38:41]
	v_mfma_f32_16x16x32_bf16 v[30:33], v[144:147], v[194:197], v[30:33]
	v_mfma_f32_16x16x32_bf16 v[22:25], v[162:165], v[194:197], v[22:25]
	v_mfma_f32_16x16x32_bf16 v[14:17], v[144:147], v[202:205], v[14:17]
	v_mfma_f32_16x16x32_bf16 v[6:9], v[162:165], v[202:205], v[6:9]
	v_mfma_f32_16x16x32_bf16 v[62:65], v[158:161], v[174:177], v[62:65]
	v_mfma_f32_16x16x32_bf16 v[54:57], v[166:169], v[174:177], v[54:57]
	v_mfma_f32_16x16x32_bf16 v[46:49], v[158:161], v[182:185], v[46:49]
	v_mfma_f32_16x16x32_bf16 v[38:41], v[166:169], v[182:185], v[38:41]
	v_mfma_f32_16x16x32_bf16 v[30:33], v[158:161], v[198:201], v[30:33]
	v_mfma_f32_16x16x32_bf16 v[22:25], v[166:169], v[198:201], v[22:25]
	v_mfma_f32_16x16x32_bf16 v[14:17], v[158:161], v[206:209], v[14:17]
	v_mfma_f32_16x16x32_bf16 v[6:9], v[166:169], v[206:209], v[6:9]
	s_setprio 0
	s_barrier
	s_add_u32 s50, s24, 0x80000
	s_addc_u32 s51, s25, 0
	s_add_i32 s49, s52, s34
	v_lshl_add_u64 v[144:145], s[50:51], 0, v[134:135]
	s_mov_b32 m0, s49
	s_nop 0
	global_load_lds_dwordx4 v[144:145], off
	v_lshl_add_u64 v[144:145], s[50:51], 0, v[130:131]
	s_add_i32 m0, s49, 0x2000
	s_nop 0
	global_load_lds_dwordx4 v[144:145], off
	s_waitcnt vmcnt(6)
	s_barrier
	s_setprio 1
	v_mfma_f32_16x16x32_bf16 v[58:61], v[210:213], v[170:173], v[58:61]
	v_mfma_f32_16x16x32_bf16 v[50:53], v[240:243], v[170:173], v[50:53]
	v_mfma_f32_16x16x32_bf16 v[42:45], v[210:213], v[178:181], v[42:45]
	v_mfma_f32_16x16x32_bf16 v[34:37], v[240:243], v[178:181], v[34:37]
	v_mfma_f32_16x16x32_bf16 v[26:29], v[210:213], v[194:197], v[26:29]
	v_mfma_f32_16x16x32_bf16 v[18:21], v[240:243], v[194:197], v[18:21]
	v_mfma_f32_16x16x32_bf16 v[10:13], v[210:213], v[202:205], v[10:13]
	v_mfma_f32_16x16x32_bf16 v[2:5], v[240:243], v[202:205], v[2:5]
	v_mfma_f32_16x16x32_bf16 v[58:61], v[236:239], v[174:177], v[58:61]
	v_mfma_f32_16x16x32_bf16 v[50:53], v[244:247], v[174:177], v[50:53]
	v_mfma_f32_16x16x32_bf16 v[42:45], v[236:239], v[182:185], v[42:45]
	v_mfma_f32_16x16x32_bf16 v[34:37], v[244:247], v[182:185], v[34:37]
	v_mfma_f32_16x16x32_bf16 v[26:29], v[236:239], v[198:201], v[26:29]
	v_mfma_f32_16x16x32_bf16 v[18:21], v[244:247], v[198:201], v[18:21]
	v_mfma_f32_16x16x32_bf16 v[10:13], v[236:239], v[206:209], v[10:13]
	v_mfma_f32_16x16x32_bf16 v[2:5], v[244:247], v[206:209], v[2:5]
	s_setprio 0
	s_add_i32 s49, 0, 0x18000
	v_add_u32_e32 v148, s49, v1
	s_barrier
	ds_read_b128 v[144:147], v148
	ds_read_b128 v[158:161], v148 offset:1024
	ds_read_b128 v[162:165], v148 offset:2048
	ds_read_b128 v[166:169], v148 offset:3072
	s_add_u32 s26, s26, 0x80000
	s_addc_u32 s27, s27, 0
	s_mov_b32 m0, s41
	v_lshl_add_u64 v[210:211], s[26:27], 0, v[136:137]
	ds_read_b128 v[170:173], v156 offset:32768
	ds_read_b128 v[174:177], v156 offset:33792
	ds_read_b128 v[178:181], v156 offset:34816
	ds_read_b128 v[182:185], v156 offset:35840
	ds_read_b128 v[194:197], v156 offset:36864
	ds_read_b128 v[198:201], v156 offset:37888
	ds_read_b128 v[202:205], v156 offset:38912
	ds_read_b128 v[206:209], v156 offset:39936
	global_load_lds_dwordx4 v[210:211], off
	v_lshl_add_u64 v[210:211], s[26:27], 0, v[132:133]
	s_mov_b32 m0, s42
	s_nop 0
	global_load_lds_dwordx4 v[210:211], off
	s_waitcnt lgkmcnt(8)
	s_barrier
	s_waitcnt lgkmcnt(0)
	s_setprio 1
	s_waitcnt lgkmcnt(0)
	v_mfma_f32_16x16x32_bf16 v[126:129], v[144:147], v[170:173], v[126:129]
	v_mfma_f32_16x16x32_bf16 v[118:121], v[162:165], v[170:173], v[118:121]
	v_mfma_f32_16x16x32_bf16 v[110:113], v[144:147], v[178:181], v[110:113]
	v_mfma_f32_16x16x32_bf16 v[102:105], v[162:165], v[178:181], v[102:105]
	v_mfma_f32_16x16x32_bf16 v[94:97], v[144:147], v[194:197], v[94:97]
	v_mfma_f32_16x16x32_bf16 v[86:89], v[162:165], v[194:197], v[86:89]
	v_mfma_f32_16x16x32_bf16 v[78:81], v[144:147], v[202:205], v[78:81]
	v_mfma_f32_16x16x32_bf16 v[70:73], v[162:165], v[202:205], v[70:73]
	v_mfma_f32_16x16x32_bf16 v[126:129], v[158:161], v[174:177], v[126:129]
	v_mfma_f32_16x16x32_bf16 v[118:121], v[166:169], v[174:177], v[118:121]
	v_mfma_f32_16x16x32_bf16 v[110:113], v[158:161], v[182:185], v[110:113]
	v_mfma_f32_16x16x32_bf16 v[102:105], v[166:169], v[182:185], v[102:105]
	v_mfma_f32_16x16x32_bf16 v[94:97], v[158:161], v[198:201], v[94:97]
	v_mfma_f32_16x16x32_bf16 v[86:89], v[166:169], v[198:201], v[86:89]
	v_mfma_f32_16x16x32_bf16 v[78:81], v[158:161], v[206:209], v[78:81]
	v_mfma_f32_16x16x32_bf16 v[70:73], v[166:169], v[206:209], v[70:73]
	s_setprio 0
	s_barrier
	s_add_i32 s26, 0, 0x1c000
	s_add_i32 s27, s49, s34
	v_add_u32_e32 v148, s26, v1
	v_lshl_add_u64 v[220:221], v[220:221], 0, s[6:7]
	s_mov_b32 m0, s27
	ds_read_b128 v[210:213], v148
	ds_read_b128 v[236:239], v148 offset:1024
	ds_read_b128 v[240:243], v148 offset:2048
	ds_read_b128 v[244:247], v148 offset:3072
	global_load_lds_dwordx4 v[220:221], off
	v_lshl_add_u64 v[220:221], v[222:223], 0, s[6:7]
	s_add_i32 m0, s27, 0x2000
	s_nop 0
	global_load_lds_dwordx4 v[220:221], off
	s_barrier
	s_waitcnt lgkmcnt(0)
	s_setprio 1
	s_waitcnt lgkmcnt(0)
	v_mfma_f32_16x16x32_bf16 v[122:125], v[210:213], v[170:173], v[122:125]
	v_mfma_f32_16x16x32_bf16 v[114:117], v[240:243], v[170:173], v[114:117]
	v_mfma_f32_16x16x32_bf16 v[106:109], v[210:213], v[178:181], v[106:109]
	v_mfma_f32_16x16x32_bf16 v[98:101], v[240:243], v[178:181], v[98:101]
	v_mfma_f32_16x16x32_bf16 v[90:93], v[210:213], v[194:197], v[90:93]
	v_mfma_f32_16x16x32_bf16 v[82:85], v[240:243], v[194:197], v[82:85]
	v_mfma_f32_16x16x32_bf16 v[74:77], v[210:213], v[202:205], v[74:77]
	v_mfma_f32_16x16x32_bf16 v[66:69], v[240:243], v[202:205], v[66:69]
	v_mfma_f32_16x16x32_bf16 v[122:125], v[236:239], v[174:177], v[122:125]
	v_mfma_f32_16x16x32_bf16 v[114:117], v[244:247], v[174:177], v[114:117]
	v_mfma_f32_16x16x32_bf16 v[106:109], v[236:239], v[182:185], v[106:109]
	v_mfma_f32_16x16x32_bf16 v[98:101], v[244:247], v[182:185], v[98:101]
	v_mfma_f32_16x16x32_bf16 v[90:93], v[236:239], v[198:201], v[90:93]
	v_mfma_f32_16x16x32_bf16 v[82:85], v[244:247], v[198:201], v[82:85]
	v_mfma_f32_16x16x32_bf16 v[74:77], v[236:239], v[206:209], v[74:77]
	v_mfma_f32_16x16x32_bf16 v[66:69], v[244:247], v[206:209], v[66:69]
	s_setprio 0
	s_mov_b32 m0, s4
	v_lshl_add_u64 v[220:221], v[248:249], 0, s[6:7]
	s_barrier
	ds_read_b128 v[170:173], v156 offset:49152
	ds_read_b128 v[174:177], v156 offset:50176
	ds_read_b128 v[178:181], v156 offset:51200
	ds_read_b128 v[182:185], v156 offset:52224
	ds_read_b128 v[194:197], v156 offset:53248
	ds_read_b128 v[198:201], v156 offset:54272
	ds_read_b128 v[202:205], v156 offset:55296
	ds_read_b128 v[206:209], v156 offset:56320
	global_load_lds_dwordx4 v[220:221], off
	v_lshl_add_u64 v[220:221], v[250:251], 0, s[6:7]
	s_mov_b32 m0, s5
	s_nop 0
	global_load_lds_dwordx4 v[220:221], off
	s_barrier
	s_waitcnt lgkmcnt(0)
	s_setprio 1
	s_waitcnt lgkmcnt(0)
	v_mfma_f32_16x16x32_bf16 v[62:65], v[144:147], v[170:173], v[62:65]
	v_mfma_f32_16x16x32_bf16 v[54:57], v[162:165], v[170:173], v[54:57]
	v_mfma_f32_16x16x32_bf16 v[46:49], v[144:147], v[178:181], v[46:49]
	v_mfma_f32_16x16x32_bf16 v[38:41], v[162:165], v[178:181], v[38:41]
	v_mfma_f32_16x16x32_bf16 v[30:33], v[144:147], v[194:197], v[30:33]
	v_mfma_f32_16x16x32_bf16 v[22:25], v[162:165], v[194:197], v[22:25]
	v_mfma_f32_16x16x32_bf16 v[14:17], v[144:147], v[202:205], v[14:17]
	v_mfma_f32_16x16x32_bf16 v[6:9], v[162:165], v[202:205], v[6:9]
	v_mfma_f32_16x16x32_bf16 v[62:65], v[158:161], v[174:177], v[62:65]
	v_mfma_f32_16x16x32_bf16 v[54:57], v[166:169], v[174:177], v[54:57]
	v_mfma_f32_16x16x32_bf16 v[46:49], v[158:161], v[182:185], v[46:49]
	v_mfma_f32_16x16x32_bf16 v[38:41], v[166:169], v[182:185], v[38:41]
	v_mfma_f32_16x16x32_bf16 v[30:33], v[158:161], v[198:201], v[30:33]
	v_mfma_f32_16x16x32_bf16 v[22:25], v[166:169], v[198:201], v[22:25]
	v_mfma_f32_16x16x32_bf16 v[14:17], v[158:161], v[206:209], v[14:17]
	v_mfma_f32_16x16x32_bf16 v[6:9], v[166:169], v[206:209], v[6:9]
	s_setprio 0
	s_barrier
	s_add_u32 s24, s24, 0x80080
	s_addc_u32 s25, s25, 0
	s_add_i32 s26, s26, s34
	v_lshl_add_u64 v[144:145], s[24:25], 0, v[134:135]
	s_mov_b32 m0, s26
	s_nop 0
	global_load_lds_dwordx4 v[144:145], off
	v_lshl_add_u64 v[144:145], s[24:25], 0, v[130:131]
	s_add_i32 m0, s26, 0x2000
	s_nop 0
	global_load_lds_dwordx4 v[144:145], off
	s_waitcnt vmcnt(6)
	s_barrier
	s_setprio 1
	v_mfma_f32_16x16x32_bf16 v[58:61], v[210:213], v[170:173], v[58:61]
	v_mfma_f32_16x16x32_bf16 v[50:53], v[240:243], v[170:173], v[50:53]
	v_mfma_f32_16x16x32_bf16 v[42:45], v[210:213], v[178:181], v[42:45]
	v_mfma_f32_16x16x32_bf16 v[34:37], v[240:243], v[178:181], v[34:37]
	v_mfma_f32_16x16x32_bf16 v[26:29], v[210:213], v[194:197], v[26:29]
	v_mfma_f32_16x16x32_bf16 v[18:21], v[240:243], v[194:197], v[18:21]
	v_mfma_f32_16x16x32_bf16 v[10:13], v[210:213], v[202:205], v[10:13]
	v_mfma_f32_16x16x32_bf16 v[2:5], v[240:243], v[202:205], v[2:5]
	v_mfma_f32_16x16x32_bf16 v[58:61], v[236:239], v[174:177], v[58:61]
	v_mfma_f32_16x16x32_bf16 v[50:53], v[244:247], v[174:177], v[50:53]
	v_mfma_f32_16x16x32_bf16 v[42:45], v[236:239], v[182:185], v[42:45]
	v_mfma_f32_16x16x32_bf16 v[34:37], v[244:247], v[182:185], v[34:37]
	v_mfma_f32_16x16x32_bf16 v[26:29], v[236:239], v[198:201], v[26:29]
	v_mfma_f32_16x16x32_bf16 v[18:21], v[244:247], v[198:201], v[18:21]
	v_mfma_f32_16x16x32_bf16 v[10:13], v[236:239], v[206:209], v[10:13]
	v_mfma_f32_16x16x32_bf16 v[2:5], v[244:247], v[206:209], v[2:5]
	s_setprio 0
	s_add_i32 s48, s48, 2
	s_add_u32 s12, s12, 0x100
	s_addc_u32 s13, s13, 0
	s_add_u32 s46, s46, 0x100
	s_addc_u32 s47, s47, 0
	s_cmp_gt_u32 s48, 29
	s_barrier
	s_cbranch_scc0 .LBB0_751
	ds_read_b32 v160, v149
	ds_read_b32 v161, v149 offset:64
	ds_read_b32 v162, v149 offset:128
	ds_read_b32 v163, v150
	ds_read_b32 v164, v151
	ds_read_b32 v165, v152
	ds_read_b32 v166, v153
	ds_read_b32 v167, v154
	s_lshl_b32 s24, s29, 8
	s_cmp_lg_u32 s29, s30
	v_add_u32_e32 v144, s24, v138
	s_cselect_b64 s[26:27], -1, 0
	s_mov_b64 s[12:13], -1
	s_and_b64 vcc, exec, s[26:27]
	v_ashrrev_i32_e32 v145, 31, v144
	s_cbranch_vccz .LBB0_754
	v_lshl_add_u64 v[146:147], v[144:145], 2, s[14:15]
	global_load_dword v146, v[146:147], off
	s_mov_b64 s[12:13], 0
	s_waitcnt vmcnt(0)
	v_fmamk_f32 v146, v146, 0x3a000000, v215
	v_mul_f32_e32 v147, 0x4b800000, v146
	v_cmp_gt_f32_e32 vcc, s65, v146
	s_nop 1
	v_cndmask_b32_e32 v146, v146, v147, vcc
	v_rsq_f32_e32 v146, v146
	s_nop 0
	v_mul_f32_e32 v147, 0x45800000, v146
	v_cndmask_b32_e32 v148, v146, v147, vcc
.LBB0_754:
	s_andn2_b64 vcc, exec, s[12:13]
	s_cbranch_vccnz .LBB0_756
	v_mov_b32_e32 v148, v160

.LBB0_758:
	s_andn2_b64 vcc, exec, s[28:29]
	s_cbranch_vccnz .LBB0_760
	v_add_u32_e32 v114, 64, v149
	v_mov_b32_e32 v114, v161

.LBB0_762:
	s_andn2_b64 vcc, exec, s[26:27]
	s_cbranch_vccnz .LBB0_764
	v_add_u32_e32 v98, 0x80, v149
	v_mov_b32_e32 v98, v162

.LBB0_766:
	s_andn2_b64 vcc, exec, s[26:27]
	s_cbranch_vccnz .LBB0_768
	v_mov_b32_e32 v82, v163

.LBB0_770:
	s_andn2_b64 vcc, exec, s[26:27]
	s_cbranch_vccnz .LBB0_772
	v_mov_b32_e32 v66, v164

.LBB0_774:
	s_andn2_b64 vcc, exec, s[26:27]
	s_cbranch_vccnz .LBB0_776
	v_mov_b32_e32 v50, v165

.LBB0_778:
	s_andn2_b64 vcc, exec, s[26:27]
	s_cbranch_vccnz .LBB0_780
	v_mov_b32_e32 v34, v166

.LBB0_782:
	s_andn2_b64 vcc, exec, s[26:27]
	s_cbranch_vccnz .LBB0_747
	v_mov_b32_e32 v18, v167
	s_branch .LBB0_747
